# grid barrier poll interval s_sleep 2 -> s_sleep 1 (otherwise identical to v45)
# speedup vs baseline: 1.0098x; 1.0098x over previous
; __device__ __forceinline__ void grid_barrier(unsigned* ctr, unsigned target) {
;     ...
;     if (threadIdx.x == 0) {
;         __builtin_amdgcn_fence(__ATOMIC_RELEASE, "agent");
;         asm volatile("s_waitcnt vmcnt(0)" ::: "memory");
;         __hip_atomic_fetch_add(ctr, 1u, __ATOMIC_RELAXED, __HIP_MEMORY_SCOPE_AGENT);
;         while (__hip_atomic_load(ctr, __ATOMIC_RELAXED, __HIP_MEMORY_SCOPE_AGENT) < target) __builtin_amdgcn_s_sleep(2);
;         __builtin_amdgcn_fence(__ATOMIC_ACQUIRE, "agent");
;         asm volatile("s_waitcnt vmcnt(0)" ::: "memory");
.LBB0_552:
	s_sleep 1
	global_load_dword v0, v149, s[6:7] sc1
	s_waitcnt vmcnt(0)
	v_cmp_gt_u32_e32 vcc, s12, v0
	s_cbranch_vccnz .LBB0_552
	s_branch .LBB0_2
